# rep-loop grid barrier arrival path: workspace-pointer s_load and first LDS read issued in front of the store drain / s_barrier instead of behind it
# speedup vs baseline: 1.0310x; 1.0049x over previous
.LBB0_1158:
	v_readlane_b32 s2, v254, 1
	v_readlane_b32 s3, v254, 2
	s_getreg_b32 s4, hwreg(HW_REG_XCC_ID, 0, 4)
	v_readlane_b32 s5, v254, 21
	s_nop 2
	s_load_dwordx2 s[2:3], s[2:3], 0x110
	v_mov_b32_e32 v0, s5
	s_nop 0
	ds_read_b32 v2, v0
	s_waitcnt vmcnt(0)
	s_waitcnt vmcnt(0) lgkmcnt(0)
	s_barrier
	s_mov_b64 s[0:1], exec
	v_readlane_b32 s6, v254, 23
	v_readlane_b32 s7, v254, 24
	s_and_b64 s[6:7], s[0:1], s[6:7]
	s_mov_b64 exec, s[6:7]
	s_cbranch_execz .LBB0_1211
	v_readlane_b32 s5, v254, 21
	s_waitcnt vmcnt(0) expcnt(0) lgkmcnt(0)
	v_readlane_b32 s5, v254, 22
	s_and_b32 s24, s4, 15
	s_waitcnt lgkmcnt(0)
	v_cmp_ne_u32_e32 vcc, 0, v2
	v_mov_b32_e32 v0, s5
	ds_read_b32 v0, v0
	s_cbranch_vccnz .LBB0_1175
	s_add_u32 s4, s2, 0x3780200
	s_addc_u32 s5, s3, 0
	s_add_u32 s6, s2, 0x3780400
	s_addc_u32 s7, s3, 0
	s_add_u32 s8, s2, 0x3780500
	s_addc_u32 s9, s3, 0
	s_add_u32 s10, s2, 0x3780600
	s_addc_u32 s11, s3, 0
	s_add_u32 s12, s2, 0x3780700
	s_addc_u32 s13, s3, 0
	s_add_u32 s14, s2, 0x3780800
	s_addc_u32 s15, s3, 0
	s_add_u32 s16, s2, 0x3780900
	s_addc_u32 s17, s3, 0
	s_add_u32 s18, s2, 0x3780a00
	s_addc_u32 s19, s3, 0
	s_add_u32 s20, s2, 0x3780b00
	s_addc_u32 s21, s3, 0
	s_add_u32 s22, s2, 0x3780c00
	s_addc_u32 s23, s3, 0
	s_add_u32 s26, s2, 0x3780d00
	s_addc_u32 s27, s3, 0
	s_add_u32 s28, s2, 0x3780e00
	s_addc_u32 s29, s3, 0
	s_add_u32 s30, s2, 0x3780f00
	s_addc_u32 s31, s3, 0
	s_add_u32 s34, s2, 0x3781000
	s_addc_u32 s35, s3, 0
	s_add_u32 s38, s2, 0x3781100
	s_addc_u32 s39, s3, 0
	s_add_u32 s40, s2, 0x3781200
	s_addc_u32 s41, s3, 0
	s_add_u32 s42, s2, 0x3781300
	s_addc_u32 s43, s3, 0
	s_mov_b32 s50, 1
	s_branch .LBB0_1163
